# GEMM tile start: accumulator zeroing with 64 v_mov_b64 instead of 128 v_mov_b32 (on top of EW LDS staging + BR epilogue)
# baseline (speedup 1.0000x reference)
;     __host__ __device__ bool next(int i, Unit& u) const { if (!base.next(i >> 1, u)) return false; if (i & 1) { u.pm += 64; u.pn += 8; } return true; }
; template <class Epi, class Sched, bool ALIGN_EPI = false, bool SP2 = false>
; __device__ __forceinline__ void gemm_phase(PG8_LAS unsigned char* lds, const Gemm g, const Sched& S, const Epi& E) {
;     ...
;     f32x4 acc[2][2][4][2];
; #pragma unroll
;     for (int a = 0; a < 2; ++a)
; #pragma unroll
;         for (int b = 0; b < 2; ++b)
; #pragma unroll
;             for (int m = 0; m < 4; ++m)
; #pragma unroll
;                 for (int n = 0; n < 2; ++n) acc[a][b][m][n] = (f32x4){0.f, 0.f, 0.f, 0.f};
;     ...
;         const bool has_next = S.next(ui + 1, nxt);
;         const char* nA = has_next ? (const char*)g.A + (size_t)nxt.pm * tstep : cA; const char* nB = has_next ? (const char*)g.Bt + (size_t)nxt.pn * tstep : cB;
;         for (int t = 0; t < nt; t += 2) {
;             const bool last = (t == nt - 2);
;             const char* a1 = cA + (size_t)(t + 1) * kstep;
;             const char* a2 = last ? nA : cA + (size_t)(t + 2) * kstep; const char* b2 = last ? nB : cB + (size_t)(t + 2) * kstep;
.LBB0_24:
	s_ashr_i32 s55, s54, 31
	s_lshl_b64 s[76:77], s[54:55], 20
	s_add_u32 s76, s8, s76
	s_addc_u32 s77, s9, s77
	s_and_b64 s[78:79], s[74:75], exec
	s_cselect_b32 s55, s77, s53
	s_cselect_b32 s83, s76, s52
	s_ashr_i32 s73, s72, 31
	s_lshl_b64 s[78:79], s[72:73], 20
	s_add_u32 s78, s0, s78
	s_addc_u32 s79, s1, s79
	s_and_b64 s[80:81], s[74:75], exec
	s_cselect_b32 s73, s79, s5
	s_cselect_b32 s84, s78, s4
	s_add_u32 s80, s52, 0x80080
	s_addc_u32 s81, s53, 0
	s_add_u32 s85, s4, 0x100
	v_mov_b64_e32 v[0:1], 0
	v_mov_b64_e32 v[2:3], 0
	v_mov_b64_e32 v[4:5], 0
	v_mov_b64_e32 v[6:7], 0
	v_mov_b64_e32 v[8:9], 0
	v_mov_b64_e32 v[10:11], 0
	v_mov_b64_e32 v[12:13], 0
	v_mov_b64_e32 v[14:15], 0
	v_mov_b64_e32 v[16:17], 0
	v_mov_b64_e32 v[18:19], 0
	v_mov_b64_e32 v[20:21], 0
	v_mov_b64_e32 v[22:23], 0
	v_mov_b64_e32 v[24:25], 0
	v_mov_b64_e32 v[26:27], 0
	v_mov_b64_e32 v[28:29], 0
	v_mov_b64_e32 v[30:31], 0
	v_mov_b64_e32 v[32:33], 0
	v_mov_b64_e32 v[34:35], 0
	v_mov_b64_e32 v[36:37], 0
	v_mov_b64_e32 v[38:39], 0
	v_mov_b64_e32 v[40:41], 0
	v_mov_b64_e32 v[42:43], 0
	v_mov_b64_e32 v[44:45], 0
	v_mov_b64_e32 v[46:47], 0
	v_mov_b64_e32 v[48:49], 0
	v_mov_b64_e32 v[50:51], 0
	v_mov_b64_e32 v[52:53], 0
	v_mov_b64_e32 v[54:55], 0
	v_mov_b64_e32 v[56:57], 0
	v_mov_b64_e32 v[58:59], 0
	v_mov_b64_e32 v[60:61], 0
	v_mov_b64_e32 v[62:63], 0
	v_mov_b64_e32 v[64:65], 0
	v_mov_b64_e32 v[66:67], 0
	v_mov_b64_e32 v[68:69], 0
	v_mov_b64_e32 v[70:71], 0
	v_mov_b64_e32 v[72:73], 0
	v_mov_b64_e32 v[74:75], 0
	v_mov_b64_e32 v[76:77], 0
	v_mov_b64_e32 v[78:79], 0
	v_mov_b64_e32 v[80:81], 0
	v_mov_b64_e32 v[82:83], 0
	v_mov_b64_e32 v[84:85], 0
	v_mov_b64_e32 v[86:87], 0
	v_mov_b64_e32 v[88:89], 0
	v_mov_b64_e32 v[90:91], 0
	v_mov_b64_e32 v[92:93], 0
	v_mov_b64_e32 v[94:95], 0
	v_mov_b64_e32 v[96:97], 0
	v_mov_b64_e32 v[98:99], 0
	v_mov_b64_e32 v[100:101], 0
	v_mov_b64_e32 v[102:103], 0
	v_mov_b64_e32 v[104:105], 0
	v_mov_b64_e32 v[106:107], 0
	v_mov_b64_e32 v[108:109], 0
	v_mov_b64_e32 v[110:111], 0
	v_mov_b64_e32 v[112:113], 0
	v_mov_b64_e32 v[114:115], 0
	v_mov_b64_e32 v[116:117], 0
	v_mov_b64_e32 v[118:119], 0
	v_mov_b64_e32 v[120:121], 0
	v_mov_b64_e32 v[122:123], 0
	v_mov_b64_e32 v[124:125], 0
	v_mov_b64_e32 v[126:127], 0
	s_addc_u32 s86, s5, 0
	s_mov_b32 s87, -2

;     __host__ __device__ bool next(int i, Unit& u) const { if (!base.next(i >> 1, u)) return false; if (i & 1) { u.pm += 64; u.pn += 8; } return true; }
; template <class Epi, class Sched, bool ALIGN_EPI = false, bool SP2 = false>
; __device__ __forceinline__ void gemm_phase(PG8_LAS unsigned char* lds, const Gemm g, const Sched& S, const Epi& E) {
;     ...
;     f32x4 acc[2][2][4][2];
; #pragma unroll
;     for (int a = 0; a < 2; ++a)
; #pragma unroll
;         for (int b = 0; b < 2; ++b)
; #pragma unroll
;             for (int m = 0; m < 4; ++m)
; #pragma unroll
;                 for (int n = 0; n < 2; ++n) acc[a][b][m][n] = (f32x4){0.f, 0.f, 0.f, 0.f};
;     ...
;         const bool has_next = S.next(ui + 1, nxt);
;         const char* nA = has_next ? (const char*)g.A + (size_t)nxt.pm * tstep : cA; const char* nB = has_next ? (const char*)g.Bt + (size_t)nxt.pn * tstep : cB;
;         for (int t = 0; t < nt; t += 2) {
;             const bool last = (t == nt - 2);
;             const char* a1 = cA + (size_t)(t + 1) * kstep;
;             const char* a2 = last ? nA : cA + (size_t)(t + 2) * kstep; const char* b2 = last ? nB : cB + (size_t)(t + 2) * kstep;
.LBB0_51:
	s_add_u32 s81, s4, 0x100
	v_mov_b64_e32 v[0:1], 0
	v_mov_b64_e32 v[2:3], 0
	v_mov_b64_e32 v[4:5], 0
	v_mov_b64_e32 v[6:7], 0
	v_mov_b64_e32 v[8:9], 0
	v_mov_b64_e32 v[10:11], 0
	v_mov_b64_e32 v[12:13], 0
	v_mov_b64_e32 v[14:15], 0
	v_mov_b64_e32 v[16:17], 0
	v_mov_b64_e32 v[18:19], 0
	v_mov_b64_e32 v[20:21], 0
	v_mov_b64_e32 v[22:23], 0
	v_mov_b64_e32 v[24:25], 0
	v_mov_b64_e32 v[26:27], 0
	v_mov_b64_e32 v[28:29], 0
	v_mov_b64_e32 v[30:31], 0
	v_mov_b64_e32 v[32:33], 0
	v_mov_b64_e32 v[34:35], 0
	v_mov_b64_e32 v[36:37], 0
	v_mov_b64_e32 v[38:39], 0
	v_mov_b64_e32 v[40:41], 0
	v_mov_b64_e32 v[42:43], 0
	v_mov_b64_e32 v[44:45], 0
	v_mov_b64_e32 v[46:47], 0
	v_mov_b64_e32 v[48:49], 0
	v_mov_b64_e32 v[50:51], 0
	v_mov_b64_e32 v[52:53], 0
	v_mov_b64_e32 v[54:55], 0
	v_mov_b64_e32 v[56:57], 0
	v_mov_b64_e32 v[58:59], 0
	v_mov_b64_e32 v[60:61], 0
	v_mov_b64_e32 v[62:63], 0
	v_mov_b64_e32 v[64:65], 0
	v_mov_b64_e32 v[66:67], 0
	v_mov_b64_e32 v[68:69], 0
	v_mov_b64_e32 v[70:71], 0
	v_mov_b64_e32 v[72:73], 0
	v_mov_b64_e32 v[74:75], 0
	v_mov_b64_e32 v[76:77], 0
	v_mov_b64_e32 v[78:79], 0
	v_mov_b64_e32 v[80:81], 0
	v_mov_b64_e32 v[82:83], 0
	v_mov_b64_e32 v[84:85], 0
	v_mov_b64_e32 v[86:87], 0
	v_mov_b64_e32 v[88:89], 0
	v_mov_b64_e32 v[90:91], 0
	v_mov_b64_e32 v[92:93], 0
	v_mov_b64_e32 v[94:95], 0
	v_mov_b64_e32 v[96:97], 0
	v_mov_b64_e32 v[98:99], 0
	v_mov_b64_e32 v[100:101], 0
	v_mov_b64_e32 v[102:103], 0
	v_mov_b64_e32 v[104:105], 0
	v_mov_b64_e32 v[106:107], 0
	v_mov_b64_e32 v[108:109], 0
	v_mov_b64_e32 v[110:111], 0
	v_mov_b64_e32 v[112:113], 0
	v_mov_b64_e32 v[114:115], 0
	v_mov_b64_e32 v[116:117], 0
	v_mov_b64_e32 v[118:119], 0
	v_mov_b64_e32 v[120:121], 0
	v_mov_b64_e32 v[122:123], 0
	v_mov_b64_e32 v[124:125], 0
	v_mov_b64_e32 v[126:127], 0
	s_addc_u32 s82, s5, 0
	s_mov_b32 s83, -2

;     __host__ __device__ bool next(int i, Unit& u) const { if (!base.next(i >> 1, u)) return false; if (i & 1) { u.pm += 64; u.pn += 8; } return true; }
; #define PG8_STAGE(bufoff, gbase, voff) do { _Pragma("unroll") for (int _i = 0; _i < 2; ++_i) \
;         __builtin_amdgcn_global_load_lds((const unsigned*)((const char*)(gbase) + (voff)[_i]), (PG8_LAS unsigned*)(lds + (bufoff) + ldsw + _i * 8192), 16, 0, 0); } while (0)
; #define PG8_WAIT_V(n) asm volatile("s_waitcnt vmcnt(" #n ")" ::: "memory")
; #define PG8_BAR __builtin_amdgcn_s_barrier()
; template <class Epi, class Sched, bool ALIGN_EPI = false, bool SP2 = false>
; __device__ __forceinline__ void gemm_phase(PG8_LAS unsigned char* lds, const Gemm g, const Sched& S, const Epi& E) {
;     ...
;     f32x4 acc[2][2][4][2];
; #pragma unroll
;     for (int a = 0; a < 2; ++a)
; #pragma unroll
;         for (int b = 0; b < 2; ++b)
; #pragma unroll
;             for (int m = 0; m < 4; ++m)
; #pragma unroll
;                 for (int n = 0; n < 2; ++n) acc[a][b][m][n] = (f32x4){0.f, 0.f, 0.f, 0.f};
;     ...
;     const char* cA = (const char*)g.A + (size_t)cur.pm * tstep; const char* cB = (const char*)g.Bt + (size_t)cur.pn * tstep;
;     S.a_ready(cur);
;     if constexpr (SP2) {
;         PG8_STAGE(PG8_SB(0, 0), cB, voffB); PG8_STAGE(PG8_SB(0, 1), cB + hstep, voffB); PG8_STAGE(PG8_SA(0, 0), cA, voffA); PG8_STAGE(PG8_SA(0, 1), cA + hstep, voffA);
;         if (wr == 1) PG8_BAR;
;         PG8_WAIT_V(2); PG8_BAR;
;         PG8_STAGE(PG8_SB(1, 0), cB + kstep, voffB); PG8_STAGE(PG8_SA(1, 0), cA + kstep, voffA); PG8_STAGE(PG8_SB(1, 1), cB + hstep + kstep, voffB);
;         PG8_WAIT_V(6); PG8_BAR;
;     } else {
;         PG8_STAGE(PG8_SB(0, 0), cB, voffB); PG8_STAGE(PG8_SA(0, 0), cA, voffA); PG8_STAGE(PG8_SB(0, 1), cB + hstep, voffB); PG8_STAGE(PG8_SA(0, 1), cA + hstep, voffA);
;         if (wr == 1) PG8_BAR;
;         PG8_WAIT_V(4); PG8_BAR;
;         PG8_STAGE(PG8_SB(1, 0), cB + kstep, voffB); PG8_STAGE(PG8_SA(1, 0), cA + kstep, voffA); PG8_STAGE(PG8_SB(1, 1), cB + hstep + kstep, voffB);
;         PG8_WAIT_V(6); PG8_BAR;
;     }
;     for (;;) {
;         const bool has_next = S.next(ui + 1, nxt);
;         const char* nA = has_next ? (const char*)g.A + (size_t)nxt.pm * tstep : cA; const char* nB = has_next ? (const char*)g.Bt + (size_t)nxt.pn * tstep : cB;
.LBB0_85:
	s_bitcmp0_b32 s7, 0
	s_cselect_b64 s[28:29], -1, 0
	s_and_b64 s[28:29], s[28:29], s[44:45]
	s_add_i32 s7, s14, 64
	s_add_i32 s15, s42, 8
	s_and_b64 s[28:29], s[28:29], exec
	s_cselect_b32 s14, s7, s14
	s_cselect_b32 s42, s15, s42
	s_ashr_i32 s15, s14, 31
	s_lshl_b64 s[28:29], s[14:15], 19
	s_add_u32 s54, s56, s28
	s_addc_u32 s55, s57, s29
	s_and_b64 s[28:29], s[44:45], exec
	s_cselect_b32 s7, s55, s53
	s_cselect_b32 s15, s54, s52
	s_ashr_i32 s43, s42, 31
	s_lshl_b64 s[28:29], s[42:43], 19
	s_add_u32 s78, s0, s28
	s_addc_u32 s79, s1, s29
	s_and_b64 s[28:29], s[44:45], exec
	s_cselect_b32 s24, s79, s5
	s_cselect_b32 s28, s78, s4
	s_add_u32 s82, s52, 0x40080
	s_addc_u32 s83, s53, 0
	s_add_u32 s29, s4, 0x100
	v_mov_b64_e32 v[0:1], 0
	v_mov_b64_e32 v[2:3], 0
	v_mov_b64_e32 v[4:5], 0
	v_mov_b64_e32 v[6:7], 0
	v_mov_b64_e32 v[8:9], 0
	v_mov_b64_e32 v[10:11], 0
	v_mov_b64_e32 v[12:13], 0
	v_mov_b64_e32 v[14:15], 0
	v_mov_b64_e32 v[16:17], 0
	v_mov_b64_e32 v[18:19], 0
	v_mov_b64_e32 v[20:21], 0
	v_mov_b64_e32 v[22:23], 0
	v_mov_b64_e32 v[24:25], 0
	v_mov_b64_e32 v[26:27], 0
	v_mov_b64_e32 v[28:29], 0
	v_mov_b64_e32 v[30:31], 0
	v_mov_b64_e32 v[32:33], 0
	v_mov_b64_e32 v[34:35], 0
	v_mov_b64_e32 v[36:37], 0
	v_mov_b64_e32 v[38:39], 0
	v_mov_b64_e32 v[40:41], 0
	v_mov_b64_e32 v[42:43], 0
	v_mov_b64_e32 v[44:45], 0
	v_mov_b64_e32 v[46:47], 0
	v_mov_b64_e32 v[48:49], 0
	v_mov_b64_e32 v[50:51], 0
	v_mov_b64_e32 v[52:53], 0
	v_mov_b64_e32 v[54:55], 0
	v_mov_b64_e32 v[56:57], 0
	v_mov_b64_e32 v[58:59], 0
	v_mov_b64_e32 v[60:61], 0
	v_mov_b64_e32 v[62:63], 0
	v_mov_b64_e32 v[64:65], 0
	v_mov_b64_e32 v[66:67], 0
	v_mov_b64_e32 v[68:69], 0
	v_mov_b64_e32 v[70:71], 0
	v_mov_b64_e32 v[72:73], 0
	v_mov_b64_e32 v[74:75], 0
	v_mov_b64_e32 v[76:77], 0
	v_mov_b64_e32 v[78:79], 0
	v_mov_b64_e32 v[80:81], 0
	v_mov_b64_e32 v[82:83], 0
	v_mov_b64_e32 v[84:85], 0
	v_mov_b64_e32 v[86:87], 0
	v_mov_b64_e32 v[88:89], 0
	v_mov_b64_e32 v[90:91], 0
	v_mov_b64_e32 v[92:93], 0
	v_mov_b64_e32 v[94:95], 0
	v_mov_b64_e32 v[96:97], 0
	v_mov_b64_e32 v[98:99], 0
	v_mov_b64_e32 v[100:101], 0
	v_mov_b64_e32 v[102:103], 0
	v_mov_b64_e32 v[104:105], 0
	v_mov_b64_e32 v[106:107], 0
	v_mov_b64_e32 v[108:109], 0
	v_mov_b64_e32 v[110:111], 0
	v_mov_b64_e32 v[112:113], 0
	v_mov_b64_e32 v[114:115], 0
	v_mov_b64_e32 v[116:117], 0
	v_mov_b64_e32 v[118:119], 0
	v_mov_b64_e32 v[120:121], 0
	v_mov_b64_e32 v[122:123], 0
	v_mov_b64_e32 v[124:125], 0
	v_mov_b64_e32 v[126:127], 0
	s_addc_u32 s43, s5, 0
	s_mov_b32 s87, -2

;     __host__ __device__ bool next(int i, Unit& u) const { if (!base.next(i >> 1, u)) return false; if (i & 1) { u.pm += 64; u.pn += 8; } return true; }
; template <class Epi, class Sched, bool ALIGN_EPI = false, bool SP2 = false>
; __device__ __forceinline__ void gemm_phase(PG8_LAS unsigned char* lds, const Gemm g, const Sched& S, const Epi& E) {
;     ...
;     f32x4 acc[2][2][4][2];
; #pragma unroll
;     for (int a = 0; a < 2; ++a)
; #pragma unroll
;         for (int b = 0; b < 2; ++b)
; #pragma unroll
;             for (int m = 0; m < 4; ++m)
; #pragma unroll
;                 for (int n = 0; n < 2; ++n) acc[a][b][m][n] = (f32x4){0.f, 0.f, 0.f, 0.f};
;     ...
;         const bool has_next = S.next(ui + 1, nxt);
;         const char* nA = has_next ? (const char*)g.A + (size_t)nxt.pm * tstep : cA; const char* nB = has_next ? (const char*)g.Bt + (size_t)nxt.pn * tstep : cB;
;         for (int t = 0; t < nt; t += 2) {
;             const bool last = (t == nt - 2);
;             const char* a1 = cA + (size_t)(t + 1) * kstep;
;             const char* a2 = last ? nA : cA + (size_t)(t + 2) * kstep; const char* b2 = last ? nB : cB + (size_t)(t + 2) * kstep;
.LBB0_321:
	s_ashr_i32 s43, s42, 31
	s_lshl_b64 s[28:29], s[42:43], 20
	s_add_u32 s94, s66, s28
	s_addc_u32 s95, s67, s29
	s_and_b64 s[28:29], s[92:93], exec
	s_cselect_b32 s1, s95, s15
	s_cselect_b32 s28, s94, s14
	s_ashr_i32 s45, s44, 31
	s_lshl_b64 s[52:53], s[44:45], 20
	s_add_u32 s96, s24, s52
	s_addc_u32 s97, s59, s53
	s_and_b64 s[52:53], s[92:93], exec
	s_cselect_b32 s29, s97, s5
	s_cselect_b32 s43, s96, s4
	s_add_u32 s14, s14, 0x80080
	s_addc_u32 s15, s15, 0
	s_add_u32 s45, s4, 0x100
	v_mov_b64_e32 v[0:1], 0
	v_mov_b64_e32 v[2:3], 0
	v_mov_b64_e32 v[4:5], 0
	v_mov_b64_e32 v[6:7], 0
	v_mov_b64_e32 v[8:9], 0
	v_mov_b64_e32 v[10:11], 0
	v_mov_b64_e32 v[12:13], 0
	v_mov_b64_e32 v[14:15], 0
	v_mov_b64_e32 v[16:17], 0
	v_mov_b64_e32 v[18:19], 0
	v_mov_b64_e32 v[20:21], 0
	v_mov_b64_e32 v[22:23], 0
	v_mov_b64_e32 v[24:25], 0
	v_mov_b64_e32 v[26:27], 0
	v_mov_b64_e32 v[28:29], 0
	v_mov_b64_e32 v[30:31], 0
	v_mov_b64_e32 v[32:33], 0
	v_mov_b64_e32 v[34:35], 0
	v_mov_b64_e32 v[36:37], 0
	v_mov_b64_e32 v[38:39], 0
	v_mov_b64_e32 v[40:41], 0
	v_mov_b64_e32 v[42:43], 0
	v_mov_b64_e32 v[44:45], 0
	v_mov_b64_e32 v[46:47], 0
	v_mov_b64_e32 v[48:49], 0
	v_mov_b64_e32 v[50:51], 0
	v_mov_b64_e32 v[52:53], 0
	v_mov_b64_e32 v[54:55], 0
	v_mov_b64_e32 v[56:57], 0
	v_mov_b64_e32 v[58:59], 0
	v_mov_b64_e32 v[60:61], 0
	v_mov_b64_e32 v[62:63], 0
	v_mov_b64_e32 v[64:65], 0
	v_mov_b64_e32 v[66:67], 0
	v_mov_b64_e32 v[68:69], 0
	v_mov_b64_e32 v[70:71], 0
	v_mov_b64_e32 v[72:73], 0
	v_mov_b64_e32 v[74:75], 0
	v_mov_b64_e32 v[76:77], 0
	v_mov_b64_e32 v[78:79], 0
	v_mov_b64_e32 v[80:81], 0
	v_mov_b64_e32 v[82:83], 0
	v_mov_b64_e32 v[84:85], 0
	v_mov_b64_e32 v[86:87], 0
	v_mov_b64_e32 v[88:89], 0
	v_mov_b64_e32 v[90:91], 0
	v_mov_b64_e32 v[92:93], 0
	v_mov_b64_e32 v[94:95], 0
	v_mov_b64_e32 v[96:97], 0
	v_mov_b64_e32 v[98:99], 0
	v_mov_b64_e32 v[100:101], 0
	v_mov_b64_e32 v[102:103], 0
	v_mov_b64_e32 v[104:105], 0
	v_mov_b64_e32 v[106:107], 0
	v_mov_b64_e32 v[108:109], 0
	v_mov_b64_e32 v[110:111], 0
	v_mov_b64_e32 v[112:113], 0
	v_mov_b64_e32 v[114:115], 0
	v_mov_b64_e32 v[116:117], 0
	v_mov_b64_e32 v[118:119], 0
	v_mov_b64_e32 v[120:121], 0
	v_mov_b64_e32 v[122:123], 0
	v_mov_b64_e32 v[124:125], 0
	v_mov_b64_e32 v[126:127], 0
	s_addc_u32 s54, s5, 0
	s_mov_b32 s55, -2

;     __host__ __device__ bool next(int i, Unit& u) const { if (!base.next(i >> 1, u)) return false; if (i & 1) { u.pm += 64; u.pn += 8; } return true; }
; template <class Epi, class Sched, bool ALIGN_EPI = false, bool SP2 = false>
; __device__ __forceinline__ void gemm_phase(PG8_LAS unsigned char* lds, const Gemm g, const Sched& S, const Epi& E) {
;     ...
;     f32x4 acc[2][2][4][2];
; #pragma unroll
;     for (int a = 0; a < 2; ++a)
; #pragma unroll
;         for (int b = 0; b < 2; ++b)
; #pragma unroll
;             for (int m = 0; m < 4; ++m)
; #pragma unroll
;                 for (int n = 0; n < 2; ++n) acc[a][b][m][n] = (f32x4){0.f, 0.f, 0.f, 0.f};
;     ...
;         const bool has_next = S.next(ui + 1, nxt);
;         const char* nA = has_next ? (const char*)g.A + (size_t)nxt.pm * tstep : cA; const char* nB = has_next ? (const char*)g.Bt + (size_t)nxt.pn * tstep : cB;
;         for (int t = 0; t < nt; t += 2) {
;             const bool last = (t == nt - 2);
;             const char* a1 = cA + (size_t)(t + 1) * kstep;
;             const char* a2 = last ? nA : cA + (size_t)(t + 2) * kstep; const char* b2 = last ? nB : cB + (size_t)(t + 2) * kstep;
.LBB0_848:
	s_ashr_i32 s11, s10, 31
	s_lshl_b64 s[42:43], s[10:11], 20
	s_add_u32 s42, s66, s42
	s_addc_u32 s43, s67, s43
	s_and_b64 s[44:45], s[14:15], exec
	s_cselect_b32 s11, s43, s53
	s_cselect_b32 s63, s42, s52
	s_ashr_i32 s13, s12, 31
	s_lshl_b64 s[44:45], s[12:13], 20
	s_add_u32 s44, s0, s44
	s_addc_u32 s45, s1, s45
	s_and_b64 s[70:71], s[14:15], exec
	s_cselect_b32 s13, s45, s5
	s_cselect_b32 s72, s44, s4
	s_add_u32 s70, s52, 0x80080
	s_addc_u32 s71, s53, 0
	s_add_u32 s73, s4, 0x100
	v_mov_b64_e32 v[0:1], 0
	v_mov_b64_e32 v[2:3], 0
	v_mov_b64_e32 v[4:5], 0
	v_mov_b64_e32 v[6:7], 0
	v_mov_b64_e32 v[8:9], 0
	v_mov_b64_e32 v[10:11], 0
	v_mov_b64_e32 v[12:13], 0
	v_mov_b64_e32 v[14:15], 0
	v_mov_b64_e32 v[16:17], 0
	v_mov_b64_e32 v[18:19], 0
	v_mov_b64_e32 v[20:21], 0
	v_mov_b64_e32 v[22:23], 0
	v_mov_b64_e32 v[24:25], 0
	v_mov_b64_e32 v[26:27], 0
	v_mov_b64_e32 v[28:29], 0
	v_mov_b64_e32 v[30:31], 0
	v_mov_b64_e32 v[32:33], 0
	v_mov_b64_e32 v[34:35], 0
	v_mov_b64_e32 v[36:37], 0
	v_mov_b64_e32 v[38:39], 0
	v_mov_b64_e32 v[40:41], 0
	v_mov_b64_e32 v[42:43], 0
	v_mov_b64_e32 v[44:45], 0
	v_mov_b64_e32 v[46:47], 0
	v_mov_b64_e32 v[48:49], 0
	v_mov_b64_e32 v[50:51], 0
	v_mov_b64_e32 v[52:53], 0
	v_mov_b64_e32 v[54:55], 0
	v_mov_b64_e32 v[56:57], 0
	v_mov_b64_e32 v[58:59], 0
	v_mov_b64_e32 v[60:61], 0
	v_mov_b64_e32 v[62:63], 0
	v_mov_b64_e32 v[64:65], 0
	v_mov_b64_e32 v[66:67], 0
	v_mov_b64_e32 v[68:69], 0
	v_mov_b64_e32 v[70:71], 0
	v_mov_b64_e32 v[72:73], 0
	v_mov_b64_e32 v[74:75], 0
	v_mov_b64_e32 v[76:77], 0
	v_mov_b64_e32 v[78:79], 0
	v_mov_b64_e32 v[80:81], 0
	v_mov_b64_e32 v[82:83], 0
	v_mov_b64_e32 v[84:85], 0
	v_mov_b64_e32 v[86:87], 0
	v_mov_b64_e32 v[88:89], 0
	v_mov_b64_e32 v[90:91], 0
	v_mov_b64_e32 v[92:93], 0
	v_mov_b64_e32 v[94:95], 0
	v_mov_b64_e32 v[96:97], 0
	v_mov_b64_e32 v[98:99], 0
	v_mov_b64_e32 v[100:101], 0
	v_mov_b64_e32 v[102:103], 0
	v_mov_b64_e32 v[104:105], 0
	v_mov_b64_e32 v[106:107], 0
	v_mov_b64_e32 v[108:109], 0
	v_mov_b64_e32 v[110:111], 0
	v_mov_b64_e32 v[112:113], 0
	v_mov_b64_e32 v[114:115], 0
	v_mov_b64_e32 v[116:117], 0
	v_mov_b64_e32 v[118:119], 0
	v_mov_b64_e32 v[120:121], 0
	v_mov_b64_e32 v[122:123], 0
	v_mov_b64_e32 v[124:125], 0
	v_mov_b64_e32 v[126:127], 0
	s_addc_u32 s74, s5, 0
	s_mov_b32 s75, -2
